# in-proj GEMM tiles 2-4 of a workgroup reuse the row scales already in LDS (same 256 tokens)
# speedup vs baseline: 1.0319x; 1.0041x over previous
; template <bool TR>
; DI void gemm_in_tile(const P& p, int l, int id, char* smem) {
;     ...
;   const int kk = id >> 8, bx = id & 255, xcd = bx & 7, s = bx >> 3;
;   const int mt = xcd * 8 + (s & 7), nt = 4 * kk + (s >> 3);
;   const int m0 = mt * 256, n0 = nt * 256;
;   constexpr bool tr = TR;
;   if (tid < 256) {
;     const float4* q = (const float4*)(p.ssq + (size_t)(m0 + tid) * 8);
;     const float4 a = q[0], b = q[1];
;     rs_s[tid] = rsqrtf((a.x + a.y + a.z + a.w + b.x + b.y + b.z + b.w) * (1.0f / 1024.0f) + 1e-6f);
;   }
.LBB0_324:
	s_and_b64 vcc, exec, s[6:7]
	s_cbranch_vccz .LBB0_102
	s_lshl_b32 s6, s88, 16
	s_lshl_b32 s7, s89, 19
	s_and_b32 s6, s6, 0x380000
	s_and_b32 s7, s7, 0x1c00000
	s_ashr_i32 s11, s88, 6
	s_or_b32 s64, s7, s6
	s_bfe_u32 s6, s88, 0x20006
	s_and_b32 s7, s11, -4
	s_lshl_b32 s10, s6, 8
	s_or_b32 s74, s7, s6
	s_cmp_lt_i32 s74, 8
	s_cselect_b64 s[6:7], -1, 0
	s_cmp_gt_i32 s74, 7
	s_cselect_b64 s[8:9], -1, 0
	s_and_b32 s56, s74, -2
	s_cmp_lg_u32 s56, 12
	s_cselect_b64 s[76:77], -1, 0
	s_and_b64 s[76:77], s[8:9], s[76:77]
	s_mov_b64 s[8:9], -1
	s_and_b64 vcc, exec, s[76:77]
	s_cbranch_vccz .LBB0_338
	s_lshl_b32 s75, s88, 3
	s_and_b32 s8, s75, 56
	s_bfe_u32 s9, s88, 0x30003
	v_mov_b32_e32 v176, v198
	s_or_b32 s78, s8, s9
	s_movk_i32 s8, 0x100
	s_lshl_b32 s76, s78, 8
	s_cmpk_gt_i32 s88, 0xff
	s_cbranch_scc1 .Lssq_skip_a
	v_cmp_gt_i32_e32 vcc, s8, v176
	s_and_saveexec_b64 s[8:9], vcc
	s_cbranch_execz .LBB0_328
	v_add_u32_e32 v0, s76, v176
	s_waitcnt lgkmcnt(0)
	v_ashrrev_i32_e32 v1, 31, v0
	v_lshlrev_b64 v[0:1], 5, v[0:1]
	v_lshl_add_u64 v[4:5], s[46:47], 0, v[0:1]
	global_load_dwordx4 v[0:3], v[4:5], off
	s_nop 0
	global_load_dwordx4 v[4:7], v[4:5], off offset:16
	s_mov_b32 s56, 0x800000
	s_waitcnt vmcnt(1)
	v_add_f32_e32 v0, v0, v1
	v_add_f32_e32 v0, v0, v2
	v_add_f32_e32 v0, v0, v3
	s_waitcnt vmcnt(0)
	v_add_f32_e32 v0, v0, v4
	v_add_f32_e32 v0, v0, v5
	v_add_f32_e32 v0, v0, v6
	v_add_f32_e32 v0, v0, v7
	v_fmamk_f32 v0, v0, 0x3a800000, v202
	v_mul_f32_e32 v1, 0x4b800000, v0
	v_cmp_gt_f32_e32 vcc, s56, v0
	s_nop 1
	v_cndmask_b32_e32 v0, v0, v1, vcc
	v_rsq_f32_e32 v0, v0
	v_lshl_add_u32 v1, v176, 2, 0
	v_add_u32_e32 v1, 0x24000, v1
	v_mul_f32_e32 v2, 0x45800000, v0
	v_cndmask_b32_e32 v0, v0, v2, vcc
	ds_write_b32 v1, v0

; template <bool AT>
; DI void gemm_main(f32x16 (&acc)[2][4], const u16* __restrict__ R, int ldr, const u16* __restrict__ Cm, int ldc,
;                   const u16* __restrict__ RT, int ldrt, int K, char* smem, int tid) {
;     ...
;   const int nk = K / 64;
; #pragma unroll
;   for (int i = 0; i < 4; ++i) {
;     const int cid = tid + NT * i;
;     const int row = cid >> 3, kc = cid & 7;
;     if (AT) {
;       const int kr = cid >> 5, tc = cid & 31;
;       rr[i] = *(const u32x4*)(RT + (size_t)kr * ldrt + tc * 8);
;     } else {
;       rr[i] = *(const u32x4*)(R + (size_t)row * ldr + kc * 8);
;     }
;     cr[i] = *(const u32x4*)(Cm + (size_t)row * ldc + kc * 8);
;   }
;   for (int kt = -1; kt < nk; ++kt) {
;     if (kt + 1 < nk) {
;       const int ks1 = kt + 1;
;       u16* Rs = S0 + (ks1 & 1) * STG;
;       u16* Cs = Rs + 256 * 72;
; #pragma unroll
;       for (int i = 0; i < 4; ++i) {
;         const int cid = tid + NT * i;
;         const int row = cid >> 3, kc = cid & 7;
;         if (AT && ks1 < 8) {
;           const int kr = cid >> 5, tc = cid & 31;
;           *(u32x4*)(Rs + kr * 264 + tc * 8) = rr[i];
;         } else {
;           *(u32x4*)(Rs + row * 72 + kc * 8) = rr[i];
;         }
;         *(u32x4*)(Cs + row * 72 + kc * 8) = cr[i];
;       }
.Lssq_skip_a:
	s_waitcnt lgkmcnt(0)
	v_lshlrev_b32_e32 v0, 3, v176
	v_and_b32_e32 v0, 56, v0
	s_lshr_b32 s77, s88, 6
	s_lshl_b32 s56, s74, 8
	s_lshl_b32 s8, s78, 19
	v_lshlrev_b32_e32 v188, 1, v0
	v_add_u32_e32 v0, 0x200, v176
	s_add_u32 s8, s36, s8
	v_ashrrev_i32_e32 v36, 3, v0
	v_add_u32_e32 v0, 0x400, v176
	s_addc_u32 s9, s37, 0
	s_lshl_b64 s[78:79], s[56:57], 11
	v_readlane_b32 s80, v248, 29
	v_ashrrev_i32_e32 v32, 3, v176
	v_ashrrev_i32_e32 v40, 3, v0
	v_add_u32_e32 v0, 0x600, v176
	s_add_u32 s78, s80, s78
	v_readlane_b32 s80, v248, 30
	v_ashrrev_i32_e32 v33, 31, v32
	v_ashrrev_i32_e32 v37, 31, v36
	v_ashrrev_i32_e32 v44, 3, v0
	s_addc_u32 s79, s80, s79
	v_lshl_add_u64 v[12:13], s[8:9], 0, v[188:189]
	v_lshlrev_b64 v[34:35], 11, v[32:33]
	v_lshlrev_b64 v[38:39], 11, v[36:37]
	v_ashrrev_i32_e32 v41, 31, v40
	v_ashrrev_i32_e32 v45, 31, v44
	v_lshl_add_u64 v[28:29], s[78:79], 0, v[188:189]
	v_lshlrev_b64 v[42:43], 11, v[40:41]
	v_lshlrev_b64 v[46:47], 11, v[44:45]
	v_lshl_add_u64 v[52:53], v[12:13], 0, v[38:39]
	v_lshl_add_u64 v[54:55], v[12:13], 0, v[34:35]
	v_lshl_add_u64 v[48:49], v[12:13], 0, v[46:47]
	v_lshl_add_u64 v[50:51], v[12:13], 0, v[42:43]
	global_load_dwordx4 v[8:11], v[52:53], off
	global_load_dwordx4 v[12:15], v[54:55], off
	v_lshl_add_u64 v[56:57], v[28:29], 0, v[34:35]
	global_load_dwordx4 v[16:19], v[56:57], off
	v_lshl_add_u64 v[58:59], v[28:29], 0, v[38:39]
	global_load_dwordx4 v[20:23], v[58:59], off
	s_waitcnt lgkmcnt(0)
	global_load_dwordx4 v[0:3], v[48:49], off
	global_load_dwordx4 v[4:7], v[50:51], off
	v_lshl_add_u64 v[60:61], v[28:29], 0, v[42:43]
	global_load_dwordx4 v[24:27], v[60:61], off
	v_lshl_add_u64 v[62:63], v[28:29], 0, v[46:47]
	global_load_dwordx4 v[28:31], v[62:63], off
	global_load_dwordx4 v[144:147], v[54:55], off offset:128
	global_load_dwordx4 v[136:139], v[52:53], off offset:128
	global_load_dwordx4 v[132:135], v[50:51], off offset:128
	global_load_dwordx4 v[128:131], v[48:49], off offset:128
	global_load_dwordx4 v[152:155], v[56:57], off offset:128
	global_load_dwordx4 v[148:151], v[58:59], off offset:128
	global_load_dwordx4 v[140:143], v[60:61], off offset:128
	global_load_dwordx4 v[156:159], v[62:63], off offset:128
	v_and_b32_e32 v177, 31, v176
	v_lshrrev_b32_e32 v33, 1, v176
	s_mov_b32 s8, 0xfffffc0
	v_and_or_b32 v45, v33, s8, v177
	s_movk_i32 s8, 0x48
	v_mul_lo_u32 v185, v32, s8
	v_mul_lo_u32 v184, v36, s8
	v_mul_lo_u32 v183, v40, s8
	v_mul_lo_u32 v182, v44, s8
	s_lshl_b32 s8, s11, 8
	s_and_b32 s8, s8, 0xfffffc00
	s_mov_b32 s9, s57
	v_add_u32_e32 v186, 0, v188
	s_or_b32 s8, s8, s10
	v_lshlrev_b32_e32 v37, 1, v176
	v_lshlrev_b32_e32 v41, 4, v176
	v_lshl_add_u32 v36, v185, 1, v186
	s_lshl_b64 s[8:9], s[8:9], 11
	v_and_b32_e32 v178, 16, v33
	v_and_or_b32 v33, v37, s95, v177
	v_lshl_add_u32 v37, v184, 1, v186
	v_lshl_add_u32 v40, v183, 1, v186
	v_lshl_add_u32 v44, v182, 1, v186
	v_mul_u32_u24_e32 v179, 0x90, v33
	v_lshl_add_u64 v[32:33], v[46:47], 0, s[8:9]
	v_mul_lo_u32 v180, v45, s94
	v_add_u32_e32 v181, 0, v178
	s_mov_b32 s78, 0
	s_waitcnt vmcnt(14)
	ds_write_b128 v36, v[12:15]
	s_waitcnt vmcnt(13)
	ds_write_b128 v36, v[16:19] offset:36864
	ds_write_b128 v37, v[8:11]
	s_waitcnt vmcnt(12)
	ds_write_b128 v37, v[20:23] offset:36864
	s_waitcnt vmcnt(10)
	ds_write_b128 v40, v[4:7]
	s_waitcnt vmcnt(9)
	ds_write_b128 v40, v[24:27] offset:36864
	ds_write_b128 v44, v[0:3]
	s_waitcnt vmcnt(8)
; DI f32x16 zero16() { f32x16 z; for (int i = 0; i < 16; ++i) z[i] = 0.f; return z; }
; template <bool AT>
; DI void gemm_main(f32x16 (&acc)[2][4], const u16* __restrict__ R, int ldr, const u16* __restrict__ Cm, int ldc,
;                   const u16* __restrict__ RT, int ldrt, int K, char* smem, int tid) {
;     ...
; #pragma unroll
;   for (int a = 0; a < 2; ++a)
; #pragma unroll
;     for (int b = 0; b < 4; ++b) acc[a][b] = zero16();
;   const int nk = K / 64;
; #pragma unroll
;   for (int i = 0; i < 4; ++i) {
;     const int cid = tid + NT * i;
;     const int row = cid >> 3, kc = cid & 7;
;     if (AT) {
;       const int kr = cid >> 5, tc = cid & 31;
;       rr[i] = *(const u32x4*)(RT + (size_t)kr * ldrt + tc * 8);
;     } else {
;       rr[i] = *(const u32x4*)(R + (size_t)row * ldr + kc * 8);
;     }
;     cr[i] = *(const u32x4*)(Cm + (size_t)row * ldc + kc * 8);
;   }
;   for (int kt = -1; kt < nk; ++kt) {
;     if (kt + 1 < nk) {
;       const int ks1 = kt + 1;
;       u16* Rs = S0 + (ks1 & 1) * STG;
;       u16* Cs = Rs + 256 * 72;
; #pragma unroll
;       for (int i = 0; i < 4; ++i) {
;         const int cid = tid + NT * i;
;         const int row = cid >> 3, kc = cid & 7;
;         if (AT && ks1 < 8) {
;           const int kr = cid >> 5, tc = cid & 31;
;           *(u32x4*)(Rs + kr * 264 + tc * 8) = rr[i];
;         } else {
;           *(u32x4*)(Rs + row * 72 + kc * 8) = rr[i];
;         }
;         *(u32x4*)(Cs + row * 72 + kc * 8) = cr[i];
;       }
;     }
;     if (kt + 2 < nk) {
;       const int kn = kt + 2;
; #pragma unroll
;       for (int i = 0; i < 4; ++i) {
;         const int cid = tid + NT * i;
;         const int row = cid >> 3, kc = cid & 7;
;         if (AT && kn < 8) {
;           const int kr = cid >> 5, tc = cid & 31;
;           rr[i] = *(const u32x4*)(RT + (size_t)(kn * 64 + kr) * ldrt + tc * 8);
;         } else {
;           rr[i] = *(const u32x4*)(R + (size_t)row * ldr + kn * 64 + kc * 8);
;         }
;         cr[i] = *(const u32x4*)(Cm + (size_t)row * ldc + kn * 64 + kc * 8);
	ds_write_b128 v44, v[28:31] offset:36864
	v_and_b32_e32 v2, 0x70, v41
	v_lshl_add_u64 v[0:1], v[42:43], 0, s[8:9]
	v_or_b32_e32 v0, v0, v2
	v_lshl_add_u64 v[162:163], s[72:73], 0, v[0:1]
	v_lshl_add_u64 v[0:1], v[38:39], 0, s[8:9]
	v_or_b32_e32 v0, v0, v2
	v_lshl_add_u64 v[164:165], s[72:73], 0, v[0:1]
	v_lshl_add_u64 v[0:1], v[34:35], 0, s[8:9]
	v_readlane_b32 s8, v248, 36
	v_or_b32_e32 v0, v0, v2
	s_add_u32 s8, s8, s64
	v_readlane_b32 s9, v248, 38
	v_or_b32_e32 v32, v32, v2
	v_lshl_add_u64 v[166:167], s[72:73], 0, v[0:1]
	v_or_b32_e32 v46, v46, v2
	s_addc_u32 s9, s9, 0
	v_or_b32_e32 v42, v42, v2
	v_or_b32_e32 v38, v38, v2
	v_or_b32_e32 v34, v34, v2
	v_mov_b32_e32 v0, 0
	v_lshl_add_u64 v[160:161], s[72:73], 0, v[32:33]
	v_lshl_add_u64 v[168:169], s[8:9], 0, v[46:47]
	v_lshl_add_u64 v[170:171], s[8:9], 0, v[42:43]
	v_lshl_add_u64 v[172:173], s[8:9], 0, v[38:39]
	v_lshl_add_u64 v[174:175], s[8:9], 0, v[34:35]
	s_mov_b64 s[8:9], 0
	v_mov_b32_e32 v1, v0
	v_mov_b32_e32 v2, v0
	v_mov_b32_e32 v3, v0
	v_mov_b32_e32 v4, v0
	v_mov_b32_e32 v5, v0
	v_mov_b32_e32 v6, v0
	v_mov_b32_e32 v7, v0
	v_mov_b32_e32 v8, v0
	v_mov_b32_e32 v9, v0
	v_mov_b32_e32 v10, v0
	v_mov_b32_e32 v11, v0
	v_mov_b32_e32 v12, v0
	v_mov_b32_e32 v13, v0
	v_mov_b32_e32 v14, v0
	v_mov_b32_e32 v15, v0
	v_mov_b32_e32 v16, v0
	v_mov_b32_e32 v17, v0
	v_mov_b32_e32 v18, v0
	v_mov_b32_e32 v19, v0
	v_mov_b32_e32 v20, v0
	v_mov_b32_e32 v21, v0
	v_mov_b32_e32 v22, v0
	v_mov_b32_e32 v23, v0
	v_mov_b32_e32 v24, v0
	v_mov_b32_e32 v25, v0
	v_mov_b32_e32 v26, v0
	v_mov_b32_e32 v27, v0
	v_mov_b32_e32 v28, v0
	v_mov_b32_e32 v29, v0
	v_mov_b32_e32 v30, v0
	v_mov_b32_e32 v31, v0
	v_mov_b32_e32 v32, v0
	v_mov_b32_e32 v33, v0
	v_mov_b32_e32 v34, v0
	v_mov_b32_e32 v35, v0
	v_mov_b32_e32 v36, v0
	v_mov_b32_e32 v37, v0
	v_mov_b32_e32 v38, v0
	v_mov_b32_e32 v39, v0
	v_mov_b32_e32 v40, v0
	v_mov_b32_e32 v41, v0
	v_mov_b32_e32 v42, v0
	v_mov_b32_e32 v43, v0
	v_mov_b32_e32 v44, v0
	v_mov_b32_e32 v45, v0
	v_mov_b32_e32 v46, v0
	v_mov_b32_e32 v47, v0
	v_mov_b32_e32 v48, v0
	v_mov_b32_e32 v49, v0
	v_mov_b32_e32 v50, v0
	v_mov_b32_e32 v51, v0
	v_mov_b32_e32 v52, v0
	v_mov_b32_e32 v53, v0
	v_mov_b32_e32 v54, v0
	v_mov_b32_e32 v55, v0
	v_mov_b32_e32 v56, v0
	v_mov_b32_e32 v57, v0
	v_mov_b32_e32 v58, v0
	v_mov_b32_e32 v59, v0
	v_mov_b32_e32 v60, v0
	v_mov_b32_e32 v61, v0
	v_mov_b32_e32 v62, v0
	v_mov_b32_e32 v63, v0
	v_mov_b32_e32 v64, v0
	v_mov_b32_e32 v65, v0
	v_mov_b32_e32 v66, v0
	v_mov_b32_e32 v67, v0
	v_mov_b32_e32 v68, v0
	v_mov_b32_e32 v69, v0
	v_mov_b32_e32 v70, v0
	v_mov_b32_e32 v71, v0
	v_mov_b32_e32 v72, v0
	v_mov_b32_e32 v73, v0
	v_mov_b32_e32 v74, v0
	v_mov_b32_e32 v75, v0
	v_mov_b32_e32 v76, v0
	v_mov_b32_e32 v77, v0
	v_mov_b32_e32 v78, v0
	v_mov_b32_e32 v79, v0
	v_mov_b32_e32 v80, v0
	v_mov_b32_e32 v81, v0
	v_mov_b32_e32 v82, v0
	v_mov_b32_e32 v83, v0
	v_mov_b32_e32 v84, v0
	v_mov_b32_e32 v85, v0
	v_mov_b32_e32 v86, v0
	v_mov_b32_e32 v87, v0
	v_mov_b32_e32 v88, v0
	v_mov_b32_e32 v89, v0
	v_mov_b32_e32 v90, v0
	v_mov_b32_e32 v91, v0
	v_mov_b32_e32 v92, v0
	v_mov_b32_e32 v93, v0
	v_mov_b32_e32 v94, v0
	v_mov_b32_e32 v95, v0
	v_mov_b32_e32 v96, v0
	v_mov_b32_e32 v97, v0
	v_mov_b32_e32 v98, v0
	v_mov_b32_e32 v99, v0
	v_mov_b32_e32 v100, v0
	v_mov_b32_e32 v101, v0
	v_mov_b32_e32 v102, v0
	v_mov_b32_e32 v103, v0
	v_mov_b32_e32 v104, v0
	v_mov_b32_e32 v105, v0
	v_mov_b32_e32 v106, v0
	v_mov_b32_e32 v107, v0
	v_mov_b32_e32 v108, v0
	v_mov_b32_e32 v109, v0
	v_mov_b32_e32 v110, v0
	v_mov_b32_e32 v111, v0
	v_mov_b32_e32 v112, v0
	v_mov_b32_e32 v113, v0
	v_mov_b32_e32 v114, v0
	v_mov_b32_e32 v115, v0
	v_mov_b32_e32 v116, v0
	v_mov_b32_e32 v117, v0
	v_mov_b32_e32 v118, v0
	v_mov_b32_e32 v119, v0
	v_mov_b32_e32 v120, v0
	v_mov_b32_e32 v121, v0
	v_mov_b32_e32 v122, v0
	v_mov_b32_e32 v123, v0
	v_mov_b32_e32 v124, v0
	v_mov_b32_e32 v125, v0
	v_mov_b32_e32 v126, v0
	v_mov_b32_e32 v127, v0
	s_waitcnt lgkmcnt(0)
	s_barrier
	v_add_u32_e32 v187, v181, v180
	v_add_u32_e32 v190, v181, v179
	v_lshl_add_u32 v191, v185, 1, v186
	v_lshl_add_u32 v196, v184, 1, v186
	v_lshl_add_u32 v197, v183, 1, v186
	v_lshl_add_u32 v249, v182, 1, v186
	v_add_u32_e32 v191, 0x12000, v191
	v_add_u32_e32 v196, 0x12000, v196
	v_add_u32_e32 v197, 0x12000, v197
	v_add_u32_e32 v249, 0x12000, v249
	s_movk_i32 s78, 7

; template <bool TR>
; DI void gemm_in_tile(const P& p, int l, int id, char* smem) {
;     ...
;   const int kk = id >> 8, bx = id & 255, xcd = bx & 7, s = bx >> 3;
;   const int mt = xcd * 8 + (s & 7), nt = 4 * kk + (s >> 3);
;   const int m0 = mt * 256, n0 = nt * 256;
;   constexpr bool tr = TR;
;   if (tid < 256) {
;     const float4* q = (const float4*)(p.ssq + (size_t)(m0 + tid) * 8);
;     const float4 a = q[0], b = q[1];
;     rs_s[tid] = rsqrtf((a.x + a.y + a.z + a.w + b.x + b.y + b.z + b.w) * (1.0f / 1024.0f) + 1e-6f);
;   }
.LBB0_338:
	s_and_b64 vcc, exec, s[8:9]
	s_cbranch_vccz .LBB0_102
	s_lshl_b32 s8, s88, 3
	s_and_b32 s75, s8, 56
	s_bfe_u32 s8, s88, 0x30003
	v_mov_b32_e32 v177, v198
	s_or_b32 s76, s75, s8
	s_movk_i32 s8, 0x100
	s_lshl_b32 s56, s76, 8
	s_cmpk_gt_i32 s88, 0xff
	s_cbranch_scc1 .Lssq_skip_b
	v_cmp_gt_i32_e32 vcc, s8, v177
	s_and_saveexec_b64 s[8:9], vcc
	s_cbranch_execz .LBB0_341
	v_add_u32_e32 v0, s56, v177
	s_waitcnt lgkmcnt(0)
	v_ashrrev_i32_e32 v1, 31, v0
	v_lshlrev_b64 v[0:1], 5, v[0:1]
	v_lshl_add_u64 v[4:5], s[46:47], 0, v[0:1]
	global_load_dwordx4 v[0:3], v[4:5], off
	s_nop 0
	global_load_dwordx4 v[4:7], v[4:5], off offset:16
	s_mov_b32 s77, 0x800000
	s_waitcnt vmcnt(1)
	v_add_f32_e32 v0, v0, v1
	v_add_f32_e32 v0, v0, v2
	v_add_f32_e32 v0, v0, v3
	s_waitcnt vmcnt(0)
	v_add_f32_e32 v0, v0, v4
	v_add_f32_e32 v0, v0, v5
	v_add_f32_e32 v0, v0, v6
	v_add_f32_e32 v0, v0, v7
	v_fmamk_f32 v0, v0, 0x3a800000, v202
	v_mul_f32_e32 v1, 0x4b800000, v0
	v_cmp_gt_f32_e32 vcc, s77, v0
	s_nop 1
	v_cndmask_b32_e32 v0, v0, v1, vcc
	v_rsq_f32_e32 v0, v0
	v_lshl_add_u32 v1, v177, 2, 0
	v_add_u32_e32 v1, 0x24000, v1
	v_mul_f32_e32 v2, 0x45800000, v0
	v_cndmask_b32_e32 v0, v0, v2, vcc
	ds_write_b32 v1, v0

; template <bool AT>
; DI void gemm_main(f32x16 (&acc)[2][4], const u16* __restrict__ R, int ldr, const u16* __restrict__ Cm, int ldc,
;                   const u16* __restrict__ RT, int ldrt, int K, char* smem, int tid) {
;     ...
;   const int nk = K / 64;
; #pragma unroll
;   for (int i = 0; i < 4; ++i) {
;     const int cid = tid + NT * i;
;     const int row = cid >> 3, kc = cid & 7;
;     if (AT) {
;       const int kr = cid >> 5, tc = cid & 31;
;       rr[i] = *(const u32x4*)(RT + (size_t)kr * ldrt + tc * 8);
;     } else {
;       rr[i] = *(const u32x4*)(R + (size_t)row * ldr + kc * 8);
;     }
;     cr[i] = *(const u32x4*)(Cm + (size_t)row * ldc + kc * 8);
;   }
;   for (int kt = -1; kt < nk; ++kt) {
;     if (kt + 1 < nk) {
;       const int ks1 = kt + 1;
;       u16* Rs = S0 + (ks1 & 1) * STG;
;       u16* Cs = Rs + 256 * 72;
; #pragma unroll
;       for (int i = 0; i < 4; ++i) {
;         const int cid = tid + NT * i;
;         const int row = cid >> 3, kc = cid & 7;
;         if (AT && ks1 < 8) {
;           const int kr = cid >> 5, tc = cid & 31;
;           *(u32x4*)(Rs + kr * 264 + tc * 8) = rr[i];
;         } else {
;           *(u32x4*)(Rs + row * 72 + kc * 8) = rr[i];
;         }
;         *(u32x4*)(Cs + row * 72 + kc * 8) = cr[i];
;       }
.Lssq_skip_b:
	s_waitcnt lgkmcnt(0)
	s_lshl_b32 s8, s74, 8
	s_lshl_b32 s9, s76, 19
	v_lshlrev_b32_e32 v0, 3, v177
	s_add_u32 s76, s36, s9
	v_and_b32_e32 v0, 56, v0
	s_addc_u32 s77, s37, 0
	v_lshlrev_b32_e32 v188, 1, v0
	s_ashr_i32 s9, s8, 31
	v_lshl_add_u64 v[20:21], s[76:77], 0, v[188:189]
	s_lshl_b64 s[76:77], s[8:9], 11
	v_readlane_b32 s9, v248, 29
	v_add_u32_e32 v8, 0x200, v177
	v_add_u32_e32 v9, 0x400, v177
	v_add_u32_e32 v10, 0x600, v177
	v_ashrrev_i32_e32 v32, 3, v177
	s_add_u32 s76, s9, s76
	v_readlane_b32 s9, v248, 30
	v_ashrrev_i32_e32 v40, 3, v8
	v_ashrrev_i32_e32 v42, 3, v9
	v_ashrrev_i32_e32 v44, 3, v10
	v_ashrrev_i32_e32 v33, 31, v32
	s_addc_u32 s77, s9, s77
	v_ashrrev_i32_e32 v41, 31, v40
	v_ashrrev_i32_e32 v43, 31, v42
	v_ashrrev_i32_e32 v45, 31, v44
	v_lshlrev_b64 v[34:35], 11, v[32:33]
	v_lshl_add_u64 v[24:25], s[76:77], 0, v[188:189]
	v_lshlrev_b64 v[46:47], 11, v[40:41]
	v_lshlrev_b64 v[52:53], 11, v[42:43]
	v_lshlrev_b64 v[56:57], 11, v[44:45]
	v_lshl_add_u64 v[36:37], v[20:21], 0, v[34:35]
	v_lshl_add_u64 v[38:39], v[24:25], 0, v[34:35]
	v_lshl_add_u64 v[48:49], v[24:25], 0, v[46:47]
	v_lshl_add_u64 v[50:51], v[20:21], 0, v[46:47]
	v_lshl_add_u64 v[54:55], v[24:25], 0, v[52:53]
	v_lshl_add_u64 v[60:61], v[20:21], 0, v[52:53]
	v_lshl_add_u64 v[62:63], v[24:25], 0, v[56:57]
	s_waitcnt lgkmcnt(0)
	global_load_dwordx4 v[0:3], v[36:37], off
	global_load_dwordx4 v[4:7], v[38:39], off
	global_load_dwordx4 v[8:11], v[48:49], off
	global_load_dwordx4 v[12:15], v[50:51], off
	global_load_dwordx4 v[16:19], v[54:55], off
	v_lshl_add_u64 v[58:59], v[20:21], 0, v[56:57]
	global_load_dwordx4 v[20:23], v[60:61], off
	global_load_dwordx4 v[24:27], v[62:63], off
	global_load_dwordx4 v[28:31], v[58:59], off
	global_load_dwordx4 v[136:139], v[36:37], off offset:128
	global_load_dwordx4 v[132:135], v[50:51], off offset:128
	global_load_dwordx4 v[128:131], v[60:61], off offset:128
	global_load_dwordx4 v[156:159], v[58:59], off offset:128
	global_load_dwordx4 v[152:155], v[38:39], off offset:128
	global_load_dwordx4 v[148:151], v[48:49], off offset:128
	global_load_dwordx4 v[144:147], v[54:55], off offset:128
	global_load_dwordx4 v[140:143], v[62:63], off offset:128
	s_movk_i32 s9, 0x48
	v_mul_lo_u32 v184, v32, s9
	v_mul_lo_u32 v185, v40, s9
	v_mul_lo_u32 v183, v42, s9
	v_mul_lo_u32 v182, v44, s9
	v_readlane_b32 s9, v248, 36
	s_add_u32 s76, s9, s64
	v_readlane_b32 s9, v248, 38
	s_addc_u32 s77, s9, 0
	s_lshl_b32 s9, s11, 8
	s_and_b32 s9, s9, 0xfffffc00
	v_ashrrev_i32_e32 v41, 1, v177
	s_or_b32 s10, s9, s10
	v_and_b32_e32 v33, 31, v177
	v_lshlrev_b32_e32 v45, 1, v177
	v_and_b32_e32 v178, 0xffffffc0, v41
	s_ashr_i32 s11, s10, 31
	v_lshlrev_b32_e32 v64, 4, v177
	v_and_or_b32 v176, v45, s95, v33
	v_or_b32_e32 v33, v178, v33
	v_add_u32_e32 v186, 0, v188
	s_lshl_b64 s[10:11], s[10:11], 11
	v_lshrrev_b32_e32 v43, 1, v177
	v_and_b32_e32 v32, 0x70, v64
	v_mul_lo_u32 v180, v33, s94
	v_lshl_add_u32 v33, v184, 1, v186
	s_add_u32 s10, s72, s10
	v_and_b32_e32 v179, 16, v43
	v_lshl_add_u32 v40, v185, 1, v186
	v_lshl_add_u32 v41, v183, 1, v186
	v_lshl_add_u32 v42, v182, 1, v186
	v_or_b32_e32 v56, v56, v32
	v_or_b32_e32 v52, v52, v32
	v_or_b32_e32 v46, v46, v32
	v_or_b32_e32 v34, v34, v32
	s_addc_u32 s11, s73, s11
	v_lshl_add_u64 v[160:161], s[76:77], 0, v[56:57]
	v_lshl_add_u64 v[162:163], s[76:77], 0, v[52:53]
	v_lshl_add_u64 v[164:165], s[76:77], 0, v[46:47]
	v_lshl_add_u64 v[166:167], s[76:77], 0, v[34:35]
	v_lshl_add_u64 v[168:169], s[10:11], 0, v[56:57]
	s_waitcnt vmcnt(15)
	ds_write_b128 v33, v[0:3] offset:36864
	s_waitcnt vmcnt(14)
	ds_write_b128 v33, v[4:7]
	s_waitcnt vmcnt(13)
	ds_write_b128 v40, v[8:11]
	s_waitcnt vmcnt(12)
	ds_write_b128 v40, v[12:15] offset:36864
	s_waitcnt vmcnt(11)
	ds_write_b128 v41, v[16:19]
	s_waitcnt vmcnt(10)
; DI f32x16 zero16() { f32x16 z; for (int i = 0; i < 16; ++i) z[i] = 0.f; return z; }
; template <bool AT>
; DI void gemm_main(f32x16 (&acc)[2][4], const u16* __restrict__ R, int ldr, const u16* __restrict__ Cm, int ldc,
;                   const u16* __restrict__ RT, int ldrt, int K, char* smem, int tid) {
;     ...
; #pragma unroll
;   for (int a = 0; a < 2; ++a)
; #pragma unroll
;     for (int b = 0; b < 4; ++b) acc[a][b] = zero16();
;   const int nk = K / 64;
; #pragma unroll
;   for (int i = 0; i < 4; ++i) {
;     const int cid = tid + NT * i;
;     const int row = cid >> 3, kc = cid & 7;
;     if (AT) {
;       const int kr = cid >> 5, tc = cid & 31;
;       rr[i] = *(const u32x4*)(RT + (size_t)kr * ldrt + tc * 8);
;     } else {
;       rr[i] = *(const u32x4*)(R + (size_t)row * ldr + kc * 8);
;     }
;     cr[i] = *(const u32x4*)(Cm + (size_t)row * ldc + kc * 8);
;   }
;   for (int kt = -1; kt < nk; ++kt) {
;     if (kt + 1 < nk) {
;       const int ks1 = kt + 1;
;       u16* Rs = S0 + (ks1 & 1) * STG;
;       u16* Cs = Rs + 256 * 72;
; #pragma unroll
;       for (int i = 0; i < 4; ++i) {
;         const int cid = tid + NT * i;
;         const int row = cid >> 3, kc = cid & 7;
;         if (AT && ks1 < 8) {
;           const int kr = cid >> 5, tc = cid & 31;
;           *(u32x4*)(Rs + kr * 264 + tc * 8) = rr[i];
;         } else {
;           *(u32x4*)(Rs + row * 72 + kc * 8) = rr[i];
;         }
;         *(u32x4*)(Cs + row * 72 + kc * 8) = cr[i];
;       }
	ds_write_b128 v41, v[20:23] offset:36864
	s_waitcnt vmcnt(9)
	ds_write_b128 v42, v[24:27]
	s_waitcnt vmcnt(8)
	ds_write_b128 v42, v[28:31] offset:36864
	v_mov_b32_e32 v0, 0
	v_lshl_add_u64 v[170:171], s[10:11], 0, v[52:53]
	v_lshl_add_u64 v[172:173], s[10:11], 0, v[46:47]
	v_lshl_add_u64 v[174:175], s[10:11], 0, v[34:35]
	s_mov_b32 s9, 0
	s_mov_b64 s[10:11], 0
	v_mov_b32_e32 v1, v0
	v_mov_b32_e32 v2, v0
	v_mov_b32_e32 v3, v0
	v_mov_b32_e32 v4, v0
	v_mov_b32_e32 v5, v0
	v_mov_b32_e32 v6, v0
	v_mov_b32_e32 v7, v0
	v_mov_b32_e32 v8, v0
	v_mov_b32_e32 v9, v0
	v_mov_b32_e32 v10, v0
	v_mov_b32_e32 v11, v0
	v_mov_b32_e32 v12, v0
	v_mov_b32_e32 v13, v0
	v_mov_b32_e32 v14, v0
	v_mov_b32_e32 v15, v0
	v_mov_b32_e32 v32, v0
	v_mov_b32_e32 v33, v0
	v_mov_b32_e32 v34, v0
	v_mov_b32_e32 v35, v0
	v_mov_b32_e32 v36, v0
	v_mov_b32_e32 v37, v0
	v_mov_b32_e32 v38, v0
	v_mov_b32_e32 v39, v0
	v_mov_b32_e32 v40, v0
	v_mov_b32_e32 v41, v0
	v_mov_b32_e32 v42, v0
	v_mov_b32_e32 v43, v0
	v_mov_b32_e32 v44, v0
	v_mov_b32_e32 v45, v0
	v_mov_b32_e32 v46, v0
	v_mov_b32_e32 v47, v0
	v_mov_b32_e32 v64, v0
	v_mov_b32_e32 v65, v0
	v_mov_b32_e32 v66, v0
	v_mov_b32_e32 v67, v0
	v_mov_b32_e32 v68, v0
	v_mov_b32_e32 v69, v0
	v_mov_b32_e32 v70, v0
	v_mov_b32_e32 v71, v0
	v_mov_b32_e32 v72, v0
	v_mov_b32_e32 v73, v0
	v_mov_b32_e32 v74, v0
	v_mov_b32_e32 v75, v0
	v_mov_b32_e32 v76, v0
	v_mov_b32_e32 v77, v0
	v_mov_b32_e32 v78, v0
	v_mov_b32_e32 v79, v0
	v_mov_b32_e32 v96, v0
	v_mov_b32_e32 v97, v0
	v_mov_b32_e32 v98, v0
	v_mov_b32_e32 v99, v0
	v_mov_b32_e32 v100, v0
	v_mov_b32_e32 v101, v0
	v_mov_b32_e32 v102, v0
	v_mov_b32_e32 v103, v0
	v_mov_b32_e32 v104, v0
	v_mov_b32_e32 v105, v0
	v_mov_b32_e32 v106, v0
	v_mov_b32_e32 v107, v0
	v_mov_b32_e32 v108, v0
	v_mov_b32_e32 v109, v0
	v_mov_b32_e32 v110, v0
	v_mov_b32_e32 v111, v0
	v_mov_b32_e32 v16, v0
	v_mov_b32_e32 v17, v0
	v_mov_b32_e32 v18, v0
	v_mov_b32_e32 v19, v0
	v_mov_b32_e32 v20, v0
	v_mov_b32_e32 v21, v0
	v_mov_b32_e32 v22, v0
	v_mov_b32_e32 v23, v0
	v_mov_b32_e32 v24, v0
	v_mov_b32_e32 v25, v0
	v_mov_b32_e32 v26, v0
	v_mov_b32_e32 v27, v0
	v_mov_b32_e32 v28, v0
	v_mov_b32_e32 v29, v0
	v_mov_b32_e32 v30, v0
	v_mov_b32_e32 v31, v0
	v_mov_b32_e32 v48, v0
	v_mov_b32_e32 v49, v0
	v_mov_b32_e32 v50, v0
	v_mov_b32_e32 v51, v0
	v_mov_b32_e32 v52, v0
	v_mov_b32_e32 v53, v0
	v_mov_b32_e32 v54, v0
	v_mov_b32_e32 v55, v0
	v_mov_b32_e32 v56, v0
	v_mov_b32_e32 v57, v0
	v_mov_b32_e32 v58, v0
	v_mov_b32_e32 v59, v0
	v_mov_b32_e32 v60, v0
	v_mov_b32_e32 v61, v0
	v_mov_b32_e32 v62, v0
	v_mov_b32_e32 v63, v0
	v_mov_b32_e32 v80, v0
	v_mov_b32_e32 v81, v0
	v_mov_b32_e32 v82, v0
	v_mov_b32_e32 v83, v0
	v_mov_b32_e32 v84, v0
	v_mov_b32_e32 v85, v0
	v_mov_b32_e32 v86, v0
	v_mov_b32_e32 v87, v0
	v_mov_b32_e32 v88, v0
	v_mov_b32_e32 v89, v0
	v_mov_b32_e32 v90, v0
	v_mov_b32_e32 v91, v0
	v_mov_b32_e32 v92, v0
	v_mov_b32_e32 v93, v0
	v_mov_b32_e32 v94, v0
	v_mov_b32_e32 v95, v0
	v_mov_b32_e32 v112, v0
	v_mov_b32_e32 v113, v0
	v_mov_b32_e32 v114, v0
	v_mov_b32_e32 v115, v0
	v_mov_b32_e32 v116, v0
	v_mov_b32_e32 v117, v0
	v_mov_b32_e32 v118, v0
	v_mov_b32_e32 v119, v0
	v_mov_b32_e32 v120, v0
	v_mov_b32_e32 v121, v0
	v_mov_b32_e32 v122, v0
	v_mov_b32_e32 v123, v0
	v_mov_b32_e32 v124, v0
	v_mov_b32_e32 v125, v0
	v_mov_b32_e32 v126, v0
	v_mov_b32_e32 v127, v0
	v_mul_u32_u24_e32 v181, 0x90, v176
	v_add_u32_e32 v187, 0, v179
	s_waitcnt lgkmcnt(0)
	s_barrier
	v_add_u32_e32 v190, v187, v180
	v_add_u32_e32 v191, v187, v181
	v_lshl_add_u32 v196, v184, 1, v186
	v_lshl_add_u32 v197, v185, 1, v186
	v_lshl_add_u32 v249, v183, 1, v186
	v_lshl_add_u32 v250, v182, 1, v186
	v_add_u32_e32 v196, 0x12000, v196
	v_add_u32_e32 v197, 0x12000, v197
	v_add_u32_e32 v249, 0x12000, v249
	v_add_u32_e32 v250, 0x12000, v250
	s_movk_i32 s64, 7
